# grid barrier 4 split: arrive, convert MLP weights, then wait for the release; plus v25 changes
# speedup vs baseline: 1.0264x; 1.0054x over previous
; __device__ __forceinline__ void xcd_barrier(const XcdBarrier& b) {
;     asm volatile("s_waitcnt vmcnt(0)" ::: "memory");
;     __syncthreads();
;     if (threadIdx.x == 0) {
;         unsigned* bar = b.bar;
;         __builtin_amdgcn_s_waitcnt(0);
;         unsigned nloc = b.st[0], nx = b.st[1];
;         if (nloc == 0u) { xcd_barrier_complete(bar, b.x, nloc, nx); b.st[0] = nloc; b.st[1] = nx; }
.LBB0_459:
	s_mov_b32 s99, 0
	s_barrier
	s_waitcnt vmcnt(0)
	v_readlane_b32 s0, v241, 0
	v_readlane_b32 s1, v241, 1
	s_barrier
	s_and_saveexec_b64 s[10:11], s[0:1]
	s_cbranch_execz .LBB0_511
	s_add_i32 s20, 0, 0x23020
	v_mov_b32_e32 v0, s20
	s_waitcnt vmcnt(0) expcnt(0) lgkmcnt(0)
	ds_read_b32 v2, v0
	s_add_i32 s20, 0, 0x23024
	v_mov_b32_e32 v0, s20
	ds_read_b32 v0, v0
	s_waitcnt lgkmcnt(1)
	v_cmp_ne_u32_e32 vcc, 0, v2
	s_cbranch_vccnz .LBB0_475
	s_mov_b32 s26, 1
	v_mov_b32_e32 v16, 0
	s_branch .LBB0_463

; __device__ __forceinline__ unsigned xb_ld(unsigned* p)              { return __hip_atomic_load(p, __ATOMIC_RELAXED, __HIP_MEMORY_SCOPE_AGENT); }
; __device__ __forceinline__ unsigned xb_add(unsigned* p, unsigned v) { return __hip_atomic_fetch_add(p, v, __ATOMIC_RELAXED, __HIP_MEMORY_SCOPE_AGENT); }
; #define XB_SPIN(cond, bar) do { unsigned _sp = 0; while (cond) { __builtin_amdgcn_s_sleep(1); \
;     if ((++_sp & 255u) == 0u) { if (xb_ld(&(bar)[XB_TMO])) break; if (_sp > XB_SPIN_CAP) { atomicAdd(&(bar)[XB_TMO], 1u); break; } } } } while (0)
; __device__ __forceinline__ void xcd_barrier(const XcdBarrier& b) {
;     ...
;         const unsigned old = xb_add(&bar[XB_XSUB(b.x)], 1u);
;         const unsigned gen = old / nloc;
;         if (old + 1u == (gen + 1u) * nloc) {
;             __builtin_amdgcn_fence(__ATOMIC_RELEASE, "agent");
;             asm volatile("s_waitcnt vmcnt(0)" ::: "memory");
;             const unsigned og = xb_add(&bar[XB_TOP], 1u);
;             const unsigned tg = og / nx;
;             if (og + 1u == (tg + 1u) * nx) xb_add(&bar[XB_TOPGEN], 1u);
;             else XB_SPIN(xb_ld(&bar[XB_TOPGEN]) == tg, bar);
;             __builtin_amdgcn_fence(__ATOMIC_ACQUIRE, "agent");
;             xb_add(&bar[XB_XGEN(b.x)], 1u);
;             asm volatile("s_waitcnt vmcnt(0)" ::: "memory");
;         } else {
;             XB_SPIN(xb_ld(&bar[XB_XGEN(b.x)]) == gen, bar);
.LBB0_477:
	s_or_b64 exec, exec, s[20:21]
	v_cvt_f32_u32_e32 v4, v2
	s_waitcnt vmcnt(0)
	v_readfirstlane_b32 s20, v3
	v_sub_u32_e32 v3, 0, v2
	v_rcp_iflag_f32_e32 v4, v4
	v_add_u32_e32 v5, s20, v1
	v_mul_f32_e32 v4, 0x4f7ffffe, v4
	v_cvt_u32_f32_e32 v4, v4
	v_mul_lo_u32 v1, v3, v4
	v_mul_hi_u32 v1, v4, v1
	v_add_u32_e32 v1, v4, v1
	v_mul_hi_u32 v1, v5, v1
	v_mul_lo_u32 v3, v1, v2
	v_sub_u32_e32 v3, v5, v3
	v_add_u32_e32 v4, 1, v1
	v_cmp_ge_u32_e32 vcc, v3, v2
	s_nop 1
	v_cndmask_b32_e32 v1, v1, v4, vcc
	v_sub_u32_e32 v4, v3, v2
	v_cndmask_b32_e32 v3, v3, v4, vcc
	v_add_u32_e32 v4, 1, v1
	v_cmp_ge_u32_e32 vcc, v3, v2
	v_add_u32_e32 v3, 1, v5
	s_nop 0
	v_cndmask_b32_e32 v1, v1, v4, vcc
	v_mul_lo_u32 v4, v2, v1
	v_add_u32_e32 v2, v4, v2
	v_cmp_ne_u32_e32 vcc, v3, v2
	s_and_saveexec_b64 s[20:21], vcc
	s_xor_b64 s[20:21], exec, s[20:21]
	s_cbranch_execz .LBB0_491
	v_readlane_b32 s0, v240, 14
	s_waitcnt lgkmcnt(0)
	v_mov_b32_e32 v0, 0
	v_readlane_b32 s1, v240, 15
	s_nop 4
	buffer_inv sc1
	v_readfirstlane_b32 s98, v1
	s_mov_b32 s99, 1
	v_cmp_ne_u32_e32 vcc, v1, v1
	s_and_saveexec_b64 s[22:23], vcc
	s_cbranch_execz .LBB0_490
	s_mov_b32 s26, 1
	s_mov_b64 s[24:25], 0
	s_branch .LBB0_481

; __device__ __forceinline__ unsigned xb_ld(unsigned* p)              { return __hip_atomic_load(p, __ATOMIC_RELAXED, __HIP_MEMORY_SCOPE_AGENT); }
; #define XB_SPIN(cond, bar) do { unsigned _sp = 0; while (cond) { __builtin_amdgcn_s_sleep(1); \
;     if ((++_sp & 255u) == 0u) { if (xb_ld(&(bar)[XB_TMO])) break; if (_sp > XB_SPIN_CAP) { atomicAdd(&(bar)[XB_TMO], 1u); break; } } } } while (0)
; __device__ __forceinline__ void ssd_state_scan(const Args& a) {
;     ...
;     for (int e = blockIdx.x * NTHREADS + tid; e < NB * 8 * 2 * 1024; e += gridDim.x * NTHREADS) {
;         const int seq = e >> 10, off = (e & 1023) * 8, dir = seq & 1, bh = seq >> 1;
;         const float* vb = vec + (size_t)bh * S_;
;         const size_t base = (size_t)seq * 8 * 8192 + off;
;         u32x4 sv[8]; float dec[8];
; __device__ __forceinline__ void xcd_barrier(const XcdBarrier& b) {
;     ...
;             XB_SPIN(xb_ld(&bar[XB_XGEN(b.x)]) == gen, bar);
;             __builtin_amdgcn_fence(__ATOMIC_ACQUIRE, "agent");
;             asm volatile("s_waitcnt vmcnt(0)" ::: "memory");
;         }
;     }
;     __syncthreads();
.LBB0_554:
	s_or_b64 exec, exec, s[20:21]
	s_cmp_eq_u32 s99, 0
	s_cbranch_scc1 .Lgb4_done
	v_readlane_b32 s100, v240, 14
	v_readlane_b32 s101, v240, 15
	s_mov_b32 s99, 0
	s_nop 3
.Lgb4_poll:
	v_mov_b32_e32 v0, 0
	global_load_dword v0, v0, s[100:101] sc1
	s_waitcnt vmcnt(0)
	v_cmp_ne_u32_e32 vcc, s98, v0
	s_cbranch_vccnz .Lgb4_done
	s_sleep 1
	s_add_i32 s99, s99, 1
	s_cmp_lt_u32 s99, 0x100000
	s_cbranch_scc1 .Lgb4_poll
.Lgb4_done:
	v_mov_b32_e32 v0, v210
	v_readlane_b32 s0, v241, 18
	s_add_u32 s42, s78, 0x1000000
	s_barrier
	s_mov_b32 s20, 0x20000
	v_add_u32_e32 v33, s0, v0
	s_addc_u32 s43, s79, 0
	v_cmp_gt_i32_e32 vcc, s20, v33
	s_and_saveexec_b64 s[20:21], vcc
	v_readlane_b32 s70, v240, 35
	v_readlane_b32 s37, v240, 34
	v_readlane_b32 s71, v240, 36
	s_mov_b64 s[64:65], s[38:39]
	s_mov_b64 s[66:67], s[96:97]
	s_mov_b64 s[68:69], s[90:91]
	s_cbranch_execz .LBB0_557
	v_lshlrev_b32_e32 v0, 3, v0
	v_mov_b32_e32 v17, 0
	v_lshl_add_u32 v37, s2, 12, v0
	s_lshl_b32 s24, s94, 12
	s_mov_b64 s[22:23], 0
	v_mov_b32_e32 v41, 0x80000
	v_mov_b32_e32 v42, 0x3fc
	v_mov_b32_e32 v43, 0x80400
	v_mov_b32_e32 v44, 0x1c000
	v_mov_b32_e32 v46, v17
	v_mov_b32_e32 v47, v17
	v_mov_b32_e32 v48, v17
	v_mov_b32_e32 v49, v17
	s_mov_b32 s25, 0x1ffff
